# attention: loop back edge rotated in front of the closing barrier; unit prologue keeps Q loads in flight across the first barrier; epilogue 1/l reads batched
# speedup vs baseline: 1.0081x; 1.0081x over previous
; __device__ __forceinline__ unsigned f2bf(float f) { return pk2(f, 0.f) & 0xffffu; }
; __device__ __forceinline__ int crow(int r, int hi) { return (r & 3) + 8 * (r >> 2) + 4 * hi; }
; __device__ __forceinline__ void ph_attn(Frame& F) {
;     ...
;         l_run += __shfl_xor(l_run, 32);
;         if (hi == 0) wsf[r32] = 1.0f / l_run;
; #pragma unroll
;         for (int r = 0; r < 16; ++r) { const int q = crow(r, hi); const float inv = wsf[q];
;             bf16* op = MIX + (size_t)(m0 + wave * 32 + q) * D + h * 64 + r32;
;             op[0] = (bf16)f2bf(o0[r] * inv); op[32] = (bf16)f2bf(o1[r] * inv); }
.LBB0_984:
	s_or_b64 exec, exec, s[10:11]
	s_waitcnt lgkmcnt(0)
	ds_read_b32 v124, v1
	ds_read_b32 v125, v1 offset:4
	ds_read_b32 v126, v1 offset:8
	ds_read_b32 v127, v1 offset:12
	ds_read_b32 v128, v1 offset:32
	ds_read_b32 v129, v1 offset:36
	ds_read_b32 v130, v1 offset:40
	ds_read_b32 v131, v1 offset:44
	ds_read_b32 v132, v1 offset:64
	ds_read_b32 v133, v1 offset:68
	ds_read_b32 v134, v1 offset:72
	ds_read_b32 v135, v1 offset:76
	ds_read_b32 v136, v1 offset:96
	ds_read_b32 v137, v1 offset:100
	ds_read_b32 v138, v1 offset:104
	ds_read_b32 v139, v1 offset:108
	s_add_i32 s10, s6, s33
	v_add_u32_e32 v38, s10, v188
	s_lshl_b32 s6, s35, 7
	v_ashrrev_i32_e32 v39, 31, v38
	v_lshl_add_u64 v[36:37], v[198:199], 0, s[6:7]
	v_lshlrev_b64 v[40:41], 11, v[38:39]
	s_waitcnt lgkmcnt(0)
	v_mul_f32_e32 v20, v20, v124
	v_mul_f32_e32 v2, v4, v124
	v_lshl_add_u64 v[40:41], v[36:37], 0, v[40:41]
	v_cvt_pk_bf16_f32 v20, v20, s0
	v_cvt_pk_bf16_f32 v2, v2, s0
	global_store_short v[40:41], v20, off
	global_store_short v[40:41], v2, off offset:64
	v_add_u32_e32 v40, s10, v203
	v_ashrrev_i32_e32 v41, 31, v40
	v_lshlrev_b64 v[40:41], 11, v[40:41]
	v_lshl_add_u64 v[40:41], v[36:37], 0, v[40:41]
	s_waitcnt lgkmcnt(0)
	v_mul_f32_e32 v4, v21, v125
	v_mul_f32_e32 v2, v5, v125
	v_cvt_pk_bf16_f32 v4, v4, s0
	v_cvt_pk_bf16_f32 v2, v2, s0
	global_store_short v[40:41], v4, off
	global_store_short v[40:41], v2, off offset:64
	v_add_u32_e32 v4, s10, v204
	v_ashrrev_i32_e32 v5, 31, v4
	v_lshlrev_b64 v[4:5], 11, v[4:5]
	v_lshl_add_u64 v[4:5], v[36:37], 0, v[4:5]
	s_waitcnt lgkmcnt(0)
	v_mul_f32_e32 v20, v22, v126
	v_mul_f32_e32 v2, v6, v126
	v_cvt_pk_bf16_f32 v20, v20, s0
	v_cvt_pk_bf16_f32 v2, v2, s0
	global_store_short v[4:5], v20, off
	global_store_short v[4:5], v2, off offset:64
	v_add_u32_e32 v4, s10, v205
	v_ashrrev_i32_e32 v5, 31, v4
	v_lshlrev_b64 v[4:5], 11, v[4:5]
	v_lshl_add_u64 v[4:5], v[36:37], 0, v[4:5]
	s_waitcnt lgkmcnt(0)
	v_mul_f32_e32 v6, v23, v127
	v_mul_f32_e32 v2, v7, v127
	v_cvt_pk_bf16_f32 v6, v6, s0
	v_cvt_pk_bf16_f32 v2, v2, s0
	global_store_short v[4:5], v6, off
	global_store_short v[4:5], v2, off offset:64
	v_add_u32_e32 v4, 8, v38
	v_ashrrev_i32_e32 v5, 31, v4
	v_lshlrev_b64 v[4:5], 11, v[4:5]
	v_lshl_add_u64 v[4:5], v[36:37], 0, v[4:5]
	s_waitcnt lgkmcnt(0)
	v_mul_f32_e32 v6, v24, v128
	v_mul_f32_e32 v2, v8, v128
	v_cvt_pk_bf16_f32 v6, v6, s0
	v_cvt_pk_bf16_f32 v2, v2, s0
	global_store_short v[4:5], v6, off
	global_store_short v[4:5], v2, off offset:64
	v_add_u32_e32 v4, 9, v38
	v_ashrrev_i32_e32 v5, 31, v4
	v_lshlrev_b64 v[4:5], 11, v[4:5]
	v_lshl_add_u64 v[4:5], v[36:37], 0, v[4:5]
	s_waitcnt lgkmcnt(0)
	v_mul_f32_e32 v6, v25, v129
	v_mul_f32_e32 v2, v9, v129
	v_cvt_pk_bf16_f32 v6, v6, s0
	v_cvt_pk_bf16_f32 v2, v2, s0
	global_store_short v[4:5], v6, off
	global_store_short v[4:5], v2, off offset:64
	v_add_u32_e32 v4, 10, v38
	v_ashrrev_i32_e32 v5, 31, v4
	v_lshlrev_b64 v[4:5], 11, v[4:5]
	v_lshl_add_u64 v[4:5], v[36:37], 0, v[4:5]
	s_waitcnt lgkmcnt(0)
	v_mul_f32_e32 v6, v26, v130
	v_mul_f32_e32 v2, v10, v130
	v_cvt_pk_bf16_f32 v6, v6, s0
	v_cvt_pk_bf16_f32 v2, v2, s0
	global_store_short v[4:5], v6, off
	global_store_short v[4:5], v2, off offset:64
	v_add_u32_e32 v4, 11, v38
	v_ashrrev_i32_e32 v5, 31, v4
	v_lshlrev_b64 v[4:5], 11, v[4:5]
	v_lshl_add_u64 v[4:5], v[36:37], 0, v[4:5]
	s_waitcnt lgkmcnt(0)
	v_mul_f32_e32 v6, v27, v131
	v_mul_f32_e32 v2, v11, v131
	v_cvt_pk_bf16_f32 v6, v6, s0
	v_cvt_pk_bf16_f32 v2, v2, s0
	global_store_short v[4:5], v6, off
	global_store_short v[4:5], v2, off offset:64
	v_add_u32_e32 v4, 16, v38
	v_ashrrev_i32_e32 v5, 31, v4
	v_lshlrev_b64 v[4:5], 11, v[4:5]
	v_lshl_add_u64 v[4:5], v[36:37], 0, v[4:5]
	s_waitcnt lgkmcnt(0)
	v_mul_f32_e32 v6, v28, v132
	v_mul_f32_e32 v2, v12, v132
	v_cvt_pk_bf16_f32 v6, v6, s0
	v_cvt_pk_bf16_f32 v2, v2, s0
	global_store_short v[4:5], v6, off
	global_store_short v[4:5], v2, off offset:64
	v_add_u32_e32 v4, 17, v38
	v_ashrrev_i32_e32 v5, 31, v4
	v_lshlrev_b64 v[4:5], 11, v[4:5]
	v_lshl_add_u64 v[4:5], v[36:37], 0, v[4:5]
	s_waitcnt lgkmcnt(0)
	v_mul_f32_e32 v6, v29, v133
	v_mul_f32_e32 v2, v13, v133
	v_cvt_pk_bf16_f32 v6, v6, s0
	v_cvt_pk_bf16_f32 v2, v2, s0
	global_store_short v[4:5], v6, off
	global_store_short v[4:5], v2, off offset:64
	v_add_u32_e32 v4, 18, v38
	v_ashrrev_i32_e32 v5, 31, v4
	v_lshlrev_b64 v[4:5], 11, v[4:5]
	v_lshl_add_u64 v[4:5], v[36:37], 0, v[4:5]
	s_waitcnt lgkmcnt(0)
	v_mul_f32_e32 v6, v30, v134
	v_mul_f32_e32 v2, v14, v134
	v_cvt_pk_bf16_f32 v6, v6, s0
	v_cvt_pk_bf16_f32 v2, v2, s0
	global_store_short v[4:5], v6, off
	global_store_short v[4:5], v2, off offset:64
	v_add_u32_e32 v4, 19, v38
	v_ashrrev_i32_e32 v5, 31, v4
	v_lshlrev_b64 v[4:5], 11, v[4:5]
	v_lshl_add_u64 v[4:5], v[36:37], 0, v[4:5]
	s_waitcnt lgkmcnt(0)
	v_mul_f32_e32 v6, v31, v135
	v_mul_f32_e32 v2, v15, v135
	v_cvt_pk_bf16_f32 v6, v6, s0
	v_cvt_pk_bf16_f32 v2, v2, s0
	global_store_short v[4:5], v6, off
	global_store_short v[4:5], v2, off offset:64
	v_add_u32_e32 v4, 24, v38
	v_ashrrev_i32_e32 v5, 31, v4
	v_lshlrev_b64 v[4:5], 11, v[4:5]
	v_lshl_add_u64 v[4:5], v[36:37], 0, v[4:5]
	s_waitcnt lgkmcnt(0)
	v_mul_f32_e32 v6, v32, v136
	v_mul_f32_e32 v2, v16, v136
	v_cvt_pk_bf16_f32 v6, v6, s0
	v_cvt_pk_bf16_f32 v2, v2, s0
	global_store_short v[4:5], v6, off
	global_store_short v[4:5], v2, off offset:64
	v_add_u32_e32 v4, 25, v38
	v_ashrrev_i32_e32 v5, 31, v4
	v_lshlrev_b64 v[4:5], 11, v[4:5]
	v_lshl_add_u64 v[4:5], v[36:37], 0, v[4:5]
	s_waitcnt lgkmcnt(0)
	v_mul_f32_e32 v6, v33, v137
	v_mul_f32_e32 v2, v17, v137
	v_cvt_pk_bf16_f32 v6, v6, s0
	v_cvt_pk_bf16_f32 v2, v2, s0
	global_store_short v[4:5], v6, off
	global_store_short v[4:5], v2, off offset:64
	v_add_u32_e32 v4, 26, v38
	v_ashrrev_i32_e32 v5, 31, v4
	v_lshlrev_b64 v[4:5], 11, v[4:5]
	v_lshl_add_u64 v[4:5], v[36:37], 0, v[4:5]
	s_waitcnt lgkmcnt(0)
	v_mul_f32_e32 v6, v34, v138
	v_mul_f32_e32 v2, v18, v138
	v_cvt_pk_bf16_f32 v6, v6, s0
	v_cvt_pk_bf16_f32 v2, v2, s0
	global_store_short v[4:5], v6, off
	global_store_short v[4:5], v2, off offset:64
	v_add_u32_e32 v4, 27, v38
	v_ashrrev_i32_e32 v5, 31, v4
	s_add_i32 s34, s34, 1
	v_lshlrev_b64 v[4:5], 11, v[4:5]
	s_waitcnt lgkmcnt(0)
	v_mul_f32_e32 v6, v35, v139
	v_mul_f32_e32 v2, v19, v139
	s_cmp_eq_u32 s34, 3
	v_lshl_add_u64 v[4:5], v[36:37], 0, v[4:5]
	v_cvt_pk_bf16_f32 v6, v6, s0
	v_cvt_pk_bf16_f32 v2, v2, s0
	s_cselect_b64 s[10:11], -1, 0
	global_store_short v[4:5], v6, off
	global_store_short v[4:5], v2, off offset:64

; #define GAS __attribute__((address_space(1)))
; #define AT_KRD(dst, koff, ks0) do { const LAS unsigned char* Kl = Kr + (koff); \
;             _Pragma("unroll") for (int ks = 0; ks < 3; ++ks) { dst[2 * ks] = *(const LAS bf16x8_t*)(Kl + ((ks0) + ks) * 32); dst[2 * ks + 1] = *(const LAS bf16x8_t*)(Kl + 32 * AT_KP + ((ks0) + ks) * 32); } } while (0)
; #define AT_ZERO(P0, P1) do { _Pragma("unroll") for (int r = 0; r < 16; ++r) { P0[r] = 0.f; P1[r] = 0.f; } } while (0)
; __device__ __forceinline__ void ph_attn(Frame& F) {
;     ...
;         if (u < 512) { b = u >> 8; h = (u >> 5) & 7; tq0 = (u & 31) * 256; NT = TQK / 64; m0 = b * SEQ + tq0; }
;         else { const int uc = u - 512; b = uc >> 3; h = uc & 7; tq0 = SEQ; NT = CTXL / 64; m0 = TL + b * CTXL; }
;         const size_t bh = (size_t)(b * 8 + h);
;         const GAS unsigned char* Kg = (const GAS unsigned char*)(Kb + bh * TQK * 96);
;         const GAS unsigned char* Vg = (const GAS unsigned char*)(Vt + bh * (TQK / 64) * 4096);
;         bf16x8_t qf[6];
;         { const bf16* qp = Qb + (bh * TQK + tq0 + wave * 32 + r32) * 96 + hi * 8;
; #pragma unroll
;           for (int ks = 0; ks < 6; ++ks) qf[ks] = *(const GAS bf16x8_t*)(qp + ks * 16); }
;         f32x16 o0, o1, pA0, pA1, pB0, pB1;
;         bf16x8_t pk0, pk1, pk2_, pk3;
;         bf16x8_t vf[8], kf[6];
;         { const v4u z = (v4u){0u, 0u, 0u, 0u}; pk0 = __builtin_bit_cast(bf16x8_t, z); pk1 = pk0; pk2_ = pk0; pk3 = pk0;
; #pragma unroll
;           for (int j = 0; j < 8; ++j) vf[j] = pk0; }
; #pragma unroll
;         for (int r = 0; r < 16; ++r) { o0[r] = 0.f; o1[r] = 0.f; pB0[r] = 0.f; pB1[r] = 0.f; }
;         float m_run = -1e30f, l_run = 0.f;
;     ...
;         asm volatile("s_waitcnt vmcnt(0)" ::: "memory");
;         __syncthreads();
;         AT_DMA(0, 0, 0, 0); AT_DMA(1, AT_KB, 1, AT_VB); AT_DMA(2, 2 * AT_KB, 0, 0); AT_DMA(3, 3 * AT_KB, 1, AT_VB);
;         asm volatile("s_waitcnt vmcnt(0)" ::: "memory");
;         __syncthreads();
;     ...
;         { bf16x8_t kg[6]; AT_KRD(kf, 0, 0); AT_KRD(kg, 0, 3); AT_ZERO(pA0, pA1); AT_KMM(pA0, pA1, kf, 0); AT_KMM(pA0, pA1, kg, 3); AT_KRD(kf, AT_KB, 0); }
;         __syncthreads();
;         if (AT_PRIO && __builtin_amdgcn_readfirstlane(wave) >= 4) __builtin_amdgcn_s_setprio(1);
.LBB0_996:
	s_and_b32 s35, s13, 7
	s_lshl_b32 s11, s12, 3
	s_or_b32 s11, s11, s35
	v_add_u32_e32 v2, s10, v201
	s_mul_hi_i32 s12, s11, 0x18c000
	s_mul_i32 s13, s11, 0x18c000
	s_mul_hi_i32 s14, s11, 0x108000
	s_mul_i32 s15, s11, 0x108000
	v_mad_i64_i32 v[4:5], s[10:11], s11, v207, v[2:3]
	v_mad_u64_u32 v[6:7], s[10:11], v4, s20, v[196:197]
	v_mad_i32_i24 v7, v5, s20, v7
	global_load_dwordx4 v[100:103], v[6:7], off
	global_load_dwordx4 v[104:107], v[6:7], off offset:32
	global_load_dwordx4 v[108:111], v[6:7], off offset:64
	global_load_dwordx4 v[112:115], v[6:7], off offset:96
	global_load_dwordx4 v[116:119], v[6:7], off offset:128
	global_load_dwordx4 v[120:123], v[6:7], off offset:160
	s_add_u32 s10, s16, s13
	s_addc_u32 s11, s17, s12
	s_add_u32 s12, s18, s15
	s_addc_u32 s13, s19, s14
	s_and_b64 s[14:15], s[4:5], exec
	s_mov_b32 m0, s22
	v_lshl_add_u64 v[4:5], s[10:11], 0, v[190:191]
	s_cselect_b32 s15, s11, s13
	s_cselect_b32 s14, s10, s12
	s_waitcnt vmcnt(6)
	s_barrier
	global_load_lds_dwordx4 v[4:5], off
	v_lshl_add_u64 v[4:5], s[14:15], 0, v[192:193]
	s_add_u32 s14, s10, 0x3000
	s_addc_u32 s15, s11, 0
	s_add_u32 s38, s12, 0x2000
	s_mov_b32 m0, s21
	s_addc_u32 s39, s13, 0
	global_load_lds_dwordx4 v[4:5], off
	v_lshl_add_u64 v[4:5], s[12:13], 0, v[194:195]
	s_mov_b32 m0, s31
	s_and_b64 s[40:41], s[4:5], exec
	global_load_lds_dwordx4 v[4:5], off
	v_lshl_add_u64 v[6:7], s[14:15], 0, v[190:191]
	s_mov_b32 m0, s24
	s_cselect_b32 s15, s15, s39
	s_cselect_b32 s14, s14, s38
	global_load_lds_dwordx4 v[6:7], off
	v_lshl_add_u64 v[6:7], s[14:15], 0, v[192:193]
	s_add_u32 s14, s10, 0x6000
	s_mov_b32 m0, s25
	s_addc_u32 s15, s11, 0
	global_load_lds_dwordx4 v[6:7], off
	v_lshl_add_u64 v[6:7], s[38:39], 0, v[194:195]
	s_mov_b32 m0, s26
	s_and_b64 s[40:41], s[4:5], exec
	global_load_lds_dwordx4 v[6:7], off
	v_lshl_add_u64 v[8:9], s[14:15], 0, v[190:191]
	s_mov_b32 m0, s27
	s_cselect_b32 s15, s15, s13
	s_cselect_b32 s14, s14, s12
	global_load_lds_dwordx4 v[8:9], off
	v_lshl_add_u64 v[8:9], s[14:15], 0, v[192:193]
	s_add_u32 s14, s10, 0x9000
	s_mov_b32 m0, s28
	s_addc_u32 s15, s11, 0
	global_load_lds_dwordx4 v[8:9], off
	s_mov_b32 m0, s31
	s_and_b64 s[40:41], s[4:5], exec
	global_load_lds_dwordx4 v[4:5], off
	v_lshl_add_u64 v[4:5], s[14:15], 0, v[190:191]
	s_mov_b32 m0, s29
	s_cselect_b32 s15, s15, s39
	s_cselect_b32 s14, s14, s38
	global_load_lds_dwordx4 v[4:5], off
	v_lshl_add_u64 v[4:5], s[14:15], 0, v[192:193]
	s_mov_b32 m0, s30
	v_readfirstlane_b32 s14, v206
	global_load_lds_dwordx4 v[4:5], off
	s_mov_b32 m0, s26
	s_cmp_lt_i32 s14, 4
	global_load_lds_dwordx4 v[6:7], off
	s_waitcnt vmcnt(0)
	s_waitcnt vmcnt(0) lgkmcnt(0)
	s_barrier
	ds_read_b128 v[4:7], v189
	ds_read_b128 v[8:11], v189 offset:32
	s_waitcnt lgkmcnt(1)
	v_mfma_f32_32x32x16_bf16 v[52:67], v[4:7], v[100:103], 0
	ds_read_b128 v[4:7], v189 offset:6656
	ds_read_b128 v[12:15], v189 offset:6688
	s_waitcnt lgkmcnt(1)
	v_mfma_f32_32x32x16_bf16 v[36:51], v[4:7], v[100:103], 0
	v_mfma_f32_32x32x16_bf16 v[52:67], v[8:11], v[104:107], v[52:67]
	ds_read_b128 v[4:7], v189 offset:64
	ds_read_b128 v[8:11], v189 offset:96
	s_waitcnt lgkmcnt(2)
	v_mfma_f32_32x32x16_bf16 v[36:51], v[12:15], v[104:107], v[36:51]
	s_waitcnt lgkmcnt(1)
	v_mfma_f32_32x32x16_bf16 v[52:67], v[4:7], v[108:111], v[52:67]
	ds_read_b128 v[4:7], v189 offset:6720
	ds_read_b128 v[12:15], v189 offset:6752
	s_waitcnt lgkmcnt(1)
	v_mfma_f32_32x32x16_bf16 v[36:51], v[4:7], v[108:111], v[36:51]
	s_waitcnt lgkmcnt(0)
	v_mfma_f32_32x32x16_bf16 v[36:51], v[12:15], v[112:115], v[36:51]
	v_mfma_f32_32x32x16_bf16 v[52:67], v[8:11], v[112:115], v[52:67]
	ds_read_b128 v[4:7], v189 offset:6784
	ds_read_b128 v[8:11], v189 offset:6816
	s_waitcnt lgkmcnt(1)
	v_mfma_f32_32x32x16_bf16 v[36:51], v[4:7], v[116:119], v[36:51]
	ds_read_b128 v[4:7], v189 offset:128
	ds_read_b128 v[12:15], v189 offset:160
	ds_read_b128 v[132:135], v189 offset:13312
	ds_read_b128 v[128:131], v189 offset:13344
	ds_read_b128 v[136:139], v189 offset:19968
	ds_read_b128 v[124:127], v189 offset:13376
	ds_read_b128 v[144:147], v189 offset:20000
	ds_read_b128 v[140:143], v189 offset:20032
	s_waitcnt lgkmcnt(0)
	s_barrier
	v_mfma_f32_32x32x16_bf16 v[52:67], v[4:7], v[116:119], v[52:67]
	v_mfma_f32_32x32x16_bf16 v[36:51], v[8:11], v[120:123], v[36:51]
	v_mfma_f32_32x32x16_bf16 v[52:67], v[12:15], v[120:123], v[52:67]
	s_cbranch_scc1 .LBB0_998
	s_setprio 1
; __device__ __forceinline__ void ph_attn(Frame& F) {
;     ...
;         f32x16 o0, o1, pA0, pA1, pB0, pB1;
;         bf16x8_t pk0, pk1, pk2_, pk3;
;         bf16x8_t vf[8], kf[6];
;         { const v4u z = (v4u){0u, 0u, 0u, 0u}; pk0 = __builtin_bit_cast(bf16x8_t, z); pk1 = pk0; pk2_ = pk0; pk3 = pk0;
; #pragma unroll
;           for (int j = 0; j < 8; ++j) vf[j] = pk0; }
; #pragma unroll
;         for (int r = 0; r < 16; ++r) { o0[r] = 0.f; o1[r] = 0.f; pB0[r] = 0.f; pB1[r] = 0.f; }
;         float m_run = -1e30f, l_run = 0.f;
;     ...
;         int kq = AT_KB, kn = 2 * AT_KB, k3 = 3 * AT_KB, kw = 0, vn = 0, v1 = AT_VB, vw = 2 * AT_VB;
.LBB0_998:
	v_mov_b32_e32 v16, v3
	v_mov_b32_e32 v17, v3
	v_mov_b32_e32 v2, v3
	v_mov_b32_e32 v4, v3
	v_mov_b32_e32 v5, v3
	v_mov_b32_e32 v6, v3
	v_mov_b32_e32 v7, v3
	v_mov_b32_e32 v8, v3
	v_mov_b32_e32 v9, v3
	v_mov_b32_e32 v10, v3
	v_mov_b32_e32 v11, v3
	v_mov_b32_e32 v12, v3
	v_mov_b32_e32 v13, v3
	v_mov_b32_e32 v14, v3
	v_mov_b32_e32 v15, v3
	v_mov_b64_e32 v[34:35], v[16:17]
	v_mov_b32_e32 v68, 0
	v_mov_b64_e32 v[32:33], v[14:15]
	v_mov_b64_e32 v[30:31], v[12:13]
	v_mov_b64_e32 v[28:29], v[10:11]
	v_mov_b64_e32 v[26:27], v[8:9]
	v_mov_b64_e32 v[24:25], v[6:7]
	v_mov_b64_e32 v[22:23], v[4:5]
	v_mov_b64_e32 v[20:21], v[2:3]
	v_mov_b64_e32 v[18:19], v[16:17]
	s_add_i32 s37, s36, -1
	s_mov_b32 s38, 0
	s_movk_i32 s40, 0x4800
	s_movk_i32 s39, 0x2400
	s_mov_b32 s41, 0x9c00
	s_movk_i32 s15, 0x6800
	s_movk_i32 s14, 0x3400
	v_mov_b32_e32 v210, 0
	s_mov_b32 s56, 0xf149f2ca
	v_mov_b32_e32 v246, 0x3f80
	v_mov_b32_e32 v247, 0
	v_mov_b32_e32 v248, 0
	v_mov_b32_e32 v249, 0
	v_mov_b32_e32 v250, 0
	v_mov_b32_e32 v251, 0
	v_mov_b32_e32 v252, 0
	v_mov_b32_e32 v253, 0
	v_cndmask_b32_e64 v246, 0, v246, s[2:3]
	v_mov_b32_e32 v209, 0
	v_mov_b64_e32 v[16:17], v[14:15]
	v_mov_b64_e32 v[14:15], v[12:13]
	v_mov_b64_e32 v[12:13], v[10:11]
	v_mov_b64_e32 v[10:11], v[8:9]
	v_mov_b64_e32 v[8:9], v[6:7]
	v_mov_b64_e32 v[6:7], v[4:5]
	v_mov_b64_e32 v[4:5], v[2:3]
	s_mov_b32 s44, 0
	s_mov_b32 s46, 0
	v_mov_b32_e32 v69, v68
	v_mov_b32_e32 v70, v68
	v_mov_b32_e32 v71, v68
	v_mov_b32_e32 v80, v68
	v_mov_b32_e32 v81, v68
	v_mov_b32_e32 v82, v68
	v_mov_b32_e32 v83, v68
	v_mov_b32_e32 v76, v68
	v_mov_b32_e32 v77, v68
	v_mov_b32_e32 v78, v68
	v_mov_b32_e32 v79, v68
	v_mov_b32_e32 v72, v68
	v_mov_b32_e32 v73, v68
	v_mov_b32_e32 v74, v68
	v_mov_b32_e32 v75, v68
	v_mov_b32_e32 v148, v68
	v_mov_b32_e32 v149, v68
	v_mov_b32_e32 v150, v68
	v_mov_b32_e32 v151, v68
	v_mov_b32_e32 v160, v68
	v_mov_b32_e32 v161, v68
	v_mov_b32_e32 v162, v68
	v_mov_b32_e32 v163, v68
	v_mov_b32_e32 v184, v68
	v_mov_b32_e32 v185, v68
	v_mov_b32_e32 v186, v68
	v_mov_b32_e32 v187, v68
	v_mov_b32_e32 v164, v68
	v_mov_b32_e32 v165, v68
	v_mov_b32_e32 v166, v68
	v_mov_b32_e32 v167, v68
	v_mov_b32_e32 v180, v68
	v_mov_b32_e32 v181, v68
	v_mov_b32_e32 v182, v68
	v_mov_b32_e32 v183, v68
	v_mov_b32_e32 v156, v68
	v_mov_b32_e32 v157, v68
	v_mov_b32_e32 v158, v68
	v_mov_b32_e32 v159, v68
	v_mov_b32_e32 v176, v68
	v_mov_b32_e32 v177, v68
	v_mov_b32_e32 v178, v68
	v_mov_b32_e32 v179, v68
	v_mov_b32_e32 v152, v68
	v_mov_b32_e32 v153, v68
	v_mov_b32_e32 v154, v68
	v_mov_b32_e32 v155, v68
	s_add_i32 s42, s46, 4
	s_min_u32 s43, s42, s37
	s_add_i32 s42, s46, 2
	s_min_u32 s45, s42, s37
	s_mulk_i32 s43, 0x3000
	s_add_u32 s48, s10, s43
	s_addc_u32 s49, s11, 0
	s_lshl_b32 s43, s45, 13
	s_add_u32 s50, s12, s43
	s_addc_u32 s51, s13, 0
	s_add_i32 m0, s22, s38
	s_and_b64 s[52:53], s[4:5], exec
.LBB0_999:
	v_lshl_add_u64 v[84:85], s[48:49], 0, v[190:191]
	s_cselect_b32 s49, s49, s51
	s_cselect_b32 s48, s48, s50
	s_cselect_b32 s43, s38, s40
	global_load_lds_dwordx4 v[84:85], off
	v_lshl_add_u64 v[84:85], s[48:49], 0, v[192:193]
	s_add_i32 m0, s21, s43
	s_add_i32 s43, s23, s40
	global_load_lds_dwordx4 v[84:85], off
	v_lshl_add_u64 v[84:85], s[50:51], 0, v[194:195]
	s_add_i32 m0, s43, 0xd000
	s_mov_b32 s43, s39
	global_load_lds_dwordx4 v[84:85], off
	s_mov_b32 s39, s44
	s_mov_b32 s44, s15
	s_mov_b32 s45, s14
	v_mfma_f32_32x32x16_bf16 v[4:19], v[68:71], v[184:187], v[4:19]
	v_max3_f32 v2, v52, v36, v53
	s_nop 0
	v_max3_f32 v2, v2, v37, v54
	s_nop 0
	v_max3_f32 v2, v2, v38, v55
	s_nop 0
	v_max3_f32 v2, v2, v39, v56
	v_mfma_f32_32x32x16_bf16 v[20:35], v[68:71], v[160:163], v[20:35]
	v_max3_f32 v68, v60, v44, v61
	v_max3_f32 v2, v2, v40, v57
	s_nop 0
	v_max3_f32 v68, v68, v45, v62
	v_max3_f32 v2, v2, v41, v58
	s_nop 0
	v_max3_f32 v68, v68, v46, v63
	v_mfma_f32_32x32x16_bf16 v[4:19], v[80:83], v[180:183], v[4:19]
	v_max3_f32 v68, v68, v47, v64
	v_max3_f32 v2, v2, v42, v59
	v_max3_f32 v68, v68, v48, v65
	s_nop 0
	v_max3_f32 v68, v68, v49, v66
	v_mfma_f32_32x32x16_bf16 v[20:35], v[80:83], v[164:167], v[20:35]
	v_max3_f32 v68, v68, v50, v67
	s_nop 0
	v_max3_f32 v2, v2, v43, v68
	s_nop 0
	v_max3_f32 v2, v2, v51, v2
	s_nop 0
	v_mov_b32_e32 v68, v2
	v_mfma_f32_32x32x16_bf16 v[4:19], v[76:79], v[176:179], v[4:19]
	v_mov_b32_e32 v69, v2
	s_nop 1
	v_permlane32_swap_b32_e32 v68, v69
	v_max3_f32 v2, v68, v69, v2
	s_nop 0
	v_cmp_lt_f32_e32 vcc, s56, v2
	v_mfma_f32_32x32x16_bf16 v[20:35], v[76:79], v[156:159], v[20:35]
	v_mfma_f32_32x32x16_bf16 v[20:35], v[72:75], v[152:155], v[20:35]
	v_mfma_f32_32x32x16_bf16 v[4:19], v[72:75], v[148:151], v[4:19]
	s_cbranch_vccz .LBB0_1003
	v_add_f32_e32 v180, v210, v2
	v_cvt_pk_bf16_f32 v180, v180, v180
	v_lshlrev_b32_e32 v180, 16, v180
	v_cndmask_b32_e32 v180, v210, v180, vcc
	v_sub_f32_e32 v2, v210, v180
	v_sub_f32_e32 v84, v180, v210
	v_xor_b32_e32 v250, 0x80000000, v180
	v_min_f32_e32 v2, 0, v2
	v_lshrrev_b32_e32 v250, 16, v250
	v_exp_f32_e32 v2, v2
	v_cndmask_b32_e64 v250, 0, v250, s[2:3]
	s_and_saveexec_b64 s[14:15], s[2:3]
	ds_write_b32 v202, v2
	s_or_b64 exec, exec, s[14:15]
	ds_read_b32 v68, v1
	ds_read_b32 v69, v1 offset:4
	ds_read_b32 v70, v1 offset:8
	ds_read_b32 v71, v1 offset:12
	ds_read_b32 v72, v1 offset:32
	ds_read_b32 v73, v1 offset:36
	ds_read_b32 v74, v1 offset:40
	ds_read_b32 v75, v1 offset:44
	ds_read_b32 v76, v1 offset:64
	ds_read_b32 v77, v1 offset:68
	ds_read_b32 v78, v1 offset:72
	ds_read_b32 v79, v1 offset:76
	ds_read_b32 v80, v1 offset:96
	ds_read_b32 v81, v1 offset:100
	ds_read_b32 v82, v1 offset:104
	ds_read_b32 v83, v1 offset:108
	v_mul_f32_e32 v209, v209, v2
	s_waitcnt lgkmcnt(0)
	v_pk_mul_f32 v[20:21], v[20:21], v[68:69]
	v_pk_mul_f32 v[22:23], v[22:23], v[70:71]
	v_pk_mul_f32 v[24:25], v[24:25], v[72:73]
	v_pk_mul_f32 v[26:27], v[26:27], v[74:75]
	v_pk_mul_f32 v[28:29], v[28:29], v[76:77]
	v_pk_mul_f32 v[30:31], v[30:31], v[78:79]
	v_pk_mul_f32 v[32:33], v[32:33], v[80:81]
	v_pk_mul_f32 v[34:35], v[34:35], v[82:83]
	v_pk_mul_f32 v[4:5], v[4:5], v[68:69]
	v_pk_mul_f32 v[6:7], v[6:7], v[70:71]
	v_pk_mul_f32 v[8:9], v[8:9], v[72:73]
	v_pk_mul_f32 v[10:11], v[10:11], v[74:75]
	v_pk_mul_f32 v[12:13], v[12:13], v[76:77]
	v_pk_mul_f32 v[14:15], v[14:15], v[78:79]
	v_pk_mul_f32 v[16:17], v[16:17], v[80:81]
	v_pk_mul_f32 v[18:19], v[18:19], v[82:83]
	v_sub_f32_e32 v36, v36, v84
	v_sub_f32_e32 v37, v37, v84
	v_sub_f32_e32 v38, v38, v84
	v_sub_f32_e32 v39, v39, v84
	v_sub_f32_e32 v40, v40, v84
	v_sub_f32_e32 v41, v41, v84
	v_sub_f32_e32 v42, v42, v84
	v_sub_f32_e32 v43, v43, v84
	v_sub_f32_e32 v44, v44, v84
	v_sub_f32_e32 v45, v45, v84
	v_sub_f32_e32 v46, v46, v84
	v_sub_f32_e32 v47, v47, v84
	v_sub_f32_e32 v48, v48, v84
	v_sub_f32_e32 v49, v49, v84
	v_sub_f32_e32 v50, v50, v84
	v_sub_f32_e32 v51, v51, v84
	v_sub_f32_e32 v52, v52, v84
	v_sub_f32_e32 v53, v53, v84
	v_sub_f32_e32 v54, v54, v84
	v_sub_f32_e32 v55, v55, v84
	v_sub_f32_e32 v56, v56, v84
	v_sub_f32_e32 v57, v57, v84
	v_sub_f32_e32 v58, v58, v84
	v_sub_f32_e32 v59, v59, v84
	v_sub_f32_e32 v60, v60, v84
	v_sub_f32_e32 v61, v61, v84
	v_sub_f32_e32 v62, v62, v84
	v_sub_f32_e32 v63, v63, v84
	v_sub_f32_e32 v64, v64, v84
	v_sub_f32_e32 v65, v65, v84
	v_sub_f32_e32 v66, v66, v84
	v_sub_f32_e32 v67, v67, v84
	s_mov_b32 s56, 0x41000000
	s_branch .LBB0_1004

; #define AT_KRD(dst, koff, ks0) do { const LAS unsigned char* Kl = Kr + (koff); \
;             _Pragma("unroll") for (int ks = 0; ks < 3; ++ks) { dst[2 * ks] = *(const LAS bf16x8_t*)(Kl + ((ks0) + ks) * 32); dst[2 * ks + 1] = *(const LAS bf16x8_t*)(Kl + 32 * AT_KP + ((ks0) + ks) * 32); } } while (0)
; #define AT_KMM(P0, P1, src, ks0) do { _Pragma("unroll") for (int ks = 0; ks < 3; ++ks) { \
;             P0 = __builtin_amdgcn_mfma_f32_32x32x16_bf16(src[2 * ks], qf[(ks0) + ks], P0, 0, 0, 0); P1 = __builtin_amdgcn_mfma_f32_32x32x16_bf16(src[2 * ks + 1], qf[(ks0) + ks], P1, 0, 0, 0); } } while (0)
; #define AT_ZERO(P0, P1) do { _Pragma("unroll") for (int r = 0; r < 16; ++r) { P0[r] = 0.f; P1[r] = 0.f; } } while (0)
; __device__ __forceinline__ void ph_attn(Frame& F) {
;     ...
;         int kq = AT_KB, kn = 2 * AT_KB, k3 = 3 * AT_KB, kw = 0, vn = 0, v1 = AT_VB, vw = 2 * AT_VB;
;         { bf16x8_t kg[6]; AT_KRD(kf, 0, 0); AT_KRD(kg, 0, 3); AT_ZERO(pA0, pA1); AT_KMM(pA0, pA1, kf, 0); AT_KMM(pA0, pA1, kg, 3); AT_KRD(kf, AT_KB, 0); }
;         __syncthreads();
;         if (AT_PRIO && __builtin_amdgcn_readfirstlane(wave) >= 4) __builtin_amdgcn_s_setprio(1);
;         for (int t = 0; t < NT; t += 2) {
;             AT_STEP(pA0, pA1, pB0, pB1, t);
;             AT_STEP(pB0, pB1, pA0, pA1, t + 1);
;         }
.LBB0_1009:
	v_mfma_f32_32x32x16_bf16 v[36:51], v[246:249], v[250:253], 0
	v_mfma_f32_32x32x16_bf16 v[36:51], v[136:139], v[100:103], v[36:51]
	v_add_u32_e32 v52, s43, v200
	ds_read_b128 v[212:215], v181 offset:96
	ds_read_b128 v[216:219], v181 offset:128
	ds_read_b128 v[220:223], v181 offset:6752
	ds_read_b128 v[224:227], v181 offset:160
	ds_read_b128 v[228:231], v181 offset:6784
	ds_read_b128 v[238:241], v181 offset:6816
	ds_read_b128 v[160:163], v52 offset:53248
	ds_read_b128 v[164:167], v52 offset:53280
	ds_read_b128 v[184:187], v52 offset:57856
	ds_read_b128 v[180:183], v52 offset:57888
	ds_read_b128 v[156:159], v52 offset:53312
	ds_read_b128 v[152:155], v52 offset:53344
	v_add_u32_e32 v209, s41, v189
	v_mfma_f32_32x32x16_bf16 v[36:51], v[148:151], v[104:107], v[36:51]
	ds_read_b128 v[176:179], v52 offset:57920
	ds_read_b128 v[148:151], v52 offset:57952
	v_exp_f32_e32 v211, v84
	v_exp_f32_e32 v232, v68
	v_exp_f32_e32 v233, v85
	v_mfma_f32_32x32x16_bf16 v[52:67], v[246:249], v[250:253], 0
	v_mfma_f32_32x32x16_bf16 v[52:67], v[144:147], v[100:103], v[52:67]
	v_exp_f32_e32 v235, v69
	v_add_f32_e32 v68, v211, v232
	v_add_f32_e32 v69, v233, v235
	v_add_f32_e32 v68, v69, v68
	v_mfma_f32_32x32x16_bf16 v[52:67], v[172:175], v[104:107], v[52:67]
	v_exp_f32_e32 v173, v70
	v_exp_f32_e32 v172, v86
	v_exp_f32_e32 v174, v87
	v_exp_f32_e32 v175, v71
	v_add_f32_e32 v69, v172, v173
	v_add_f32_e32 v68, v69, v68
	v_mfma_f32_32x32x16_bf16 v[52:67], v[168:171], v[108:111], v[52:67]
	v_add_f32_e32 v69, v174, v175
	v_add_f32_e32 v168, v69, v68
	v_exp_f32_e32 v71, v88
	v_exp_f32_e32 v85, v72
	v_exp_f32_e32 v70, v89
	v_exp_f32_e32 v84, v73
	v_exp_f32_e32 v73, v90
	v_exp_f32_e32 v87, v74
	v_exp_f32_e32 v72, v91
	v_exp_f32_e32 v86, v75
	v_pk_add_f32 v[68:69], v[70:71], v[84:85]
	v_mfma_f32_32x32x16_bf16 v[36:51], v[140:143], v[108:111], v[36:51]
	v_add_f32_e32 v69, v69, v168
	v_add_f32_e32 v74, v68, v69
	v_add_f32_e64 v68, v72, v86
	v_add_f32_e64 v69, v73, v87
	ds_read_b128 v[132:135], v209
	ds_read_b128 v[128:131], v209 offset:32
	ds_read_b128 v[136:139], v209 offset:6656
	ds_read_b128 v[124:127], v209 offset:64
	v_add_f32_e32 v69, v69, v74
	v_add_f32_e32 v168, v68, v69
	v_exp_f32_e32 v75, v92
	v_exp_f32_e32 v89, v76
	v_exp_f32_e32 v74, v93
	v_exp_f32_e32 v88, v77
	v_exp_f32_e32 v77, v94
	s_waitcnt lgkmcnt(12)
	v_mfma_f32_32x32x16_bf16 v[36:51], v[220:223], v[112:115], v[36:51]
	v_exp_f32_e32 v91, v78
	v_exp_f32_e32 v76, v95
	v_exp_f32_e32 v90, v79
	v_pk_add_f32 v[68:69], v[74:75], v[88:89]
	ds_read_b128 v[144:147], v209 offset:6688
	ds_read_b128 v[140:143], v209 offset:6720
	v_mfma_f32_32x32x16_bf16 v[52:67], v[212:215], v[112:115], v[52:67]
	v_add_f32_e32 v69, v69, v168
	v_add_f32_e32 v78, v68, v69
	v_add_f32_e64 v68, v76, v90
	v_add_f32_e64 v69, v77, v91
	v_add_f32_e32 v69, v69, v78
	v_add_f32_e32 v168, v68, v69
	v_mfma_f32_32x32x16_bf16 v[36:51], v[228:231], v[116:119], v[36:51]
	v_exp_f32_e32 v79, v96
	v_exp_f32_e32 v93, v80
	v_exp_f32_e32 v78, v97
	v_exp_f32_e32 v92, v81
	v_mfma_f32_32x32x16_bf16 v[52:67], v[216:219], v[116:119], v[52:67]
	v_exp_f32_e32 v95, v98
	v_exp_f32_e32 v97, v82
	v_exp_f32_e32 v94, v99
	v_mfma_f32_32x32x16_bf16 v[36:51], v[238:241], v[120:123], v[36:51]
	v_exp_f32_e32 v96, v83
	v_pk_add_f32 v[68:69], v[78:79], v[92:93]
	s_nop 0
	v_add_f32_e32 v69, v69, v168
	v_add_f32_e32 v80, v68, v69
	v_pk_add_f32 v[68:69], v[94:95], v[96:97]
	v_mfma_f32_32x32x16_bf16 v[52:67], v[224:227], v[120:123], v[52:67]
	v_add_f32_e32 v69, v69, v80
	v_add_f32_e32 v68, v68, v69
	v_add_f32_e32 v209, v2, v68
	v_cvt_pk_bf16_f32 v68, v211, v233
	v_cvt_pk_bf16_f32 v69, v172, v174
	v_cvt_pk_bf16_f32 v70, v71, v70
	v_cvt_pk_bf16_f32 v71, v73, v72
	v_cvt_pk_bf16_f32 v80, v75, v74
	v_cvt_pk_bf16_f32 v81, v77, v76
	v_cvt_pk_bf16_f32 v82, v79, v78
	v_cvt_pk_bf16_f32 v83, v95, v94
	v_cvt_pk_bf16_f32 v76, v232, v235
	v_cvt_pk_bf16_f32 v77, v173, v175
	v_cvt_pk_bf16_f32 v78, v85, v84
	v_cvt_pk_bf16_f32 v79, v87, v86
	v_cvt_pk_bf16_f32 v72, v89, v88
	v_cvt_pk_bf16_f32 v73, v91, v90
	v_cvt_pk_bf16_f32 v74, v93, v92
	v_cvt_pk_bf16_f32 v75, v97, v96
	s_cmp_ge_u32 s42, s36
	s_cbranch_scc1 .Lattn_exit
	s_mov_b32 s14, s41
	s_mov_b32 s15, s38
	s_mov_b32 s41, s45
	s_mov_b32 s38, s44
	s_mov_b32 s44, s40
	s_mov_b32 s40, s43
	s_mov_b32 s46, s42
	s_add_i32 s42, s46, 4
	s_min_u32 s43, s42, s37
	s_add_i32 s42, s46, 2
	s_min_u32 s45, s42, s37
	s_mulk_i32 s43, 0x3000
	s_add_u32 s48, s10, s43
	s_addc_u32 s49, s11, 0
	s_lshl_b32 s43, s45, 13
	s_add_u32 s50, s12, s43
	s_addc_u32 s51, s13, 0
	s_add_i32 m0, s22, s38
	s_and_b64 s[52:53], s[4:5], exec
	s_waitcnt vmcnt(3) lgkmcnt(0)
	s_barrier
	s_branch .LBB0_999
.Lattn_exit:
	s_waitcnt vmcnt(3) lgkmcnt(0)
	s_barrier
